# split-K tail owners poll the producers' counter without the sleep between polls
# speedup vs baseline: 1.0017x; 1.0017x over previous
; #define LAS __attribute__((address_space(3)))
; template <class Epi, int LDA, int LDB, int KK>
; __device__ __forceinline__ void gemm_phase(int wv, LAS unsigned char* lds, const Gemm g, const StaticOrder& S, const Epi& E) {
;     ...
;           if constexpr (Epi::HAS_MID) { if (seg < Epi::NSEG - 1) E.mid(acc, cur, seg, wr, wc, fr, fq); }
;         }
;         E(acc, cur, wr, wc, fr, fq, (const LAS float*)(lds + 131072 + (ui % 3) * 1024));
.Lmt_poll:
	s_sleep 0
	global_load_dword v133, v132, s[98:99] sc1
	s_waitcnt vmcnt(0)
	v_cmp_gt_u32_e32 vcc, s23, v133
	s_cbranch_vccnz .Lmt_poll
	buffer_inv sc1
	s_waitcnt vmcnt(0)
	s_mov_b64 exec, -1

; #define LAS __attribute__((address_space(3)))
; template <class Epi, int LDA, int LDB, int KK>
; __device__ __forceinline__ void gemm_phase(int wv, LAS unsigned char* lds, const Gemm g, const StaticOrder& S, const Epi& E) {
;     ...
;           if constexpr (Epi::HAS_MID) { if (seg < Epi::NSEG - 1) E.mid(acc, cur, seg, wr, wc, fr, fq); }
;         }
;         E(acc, cur, wr, wc, fr, fq, (const LAS float*)(lds + 131072 + (ui % 3) * 1024));
.Lot_poll:
	s_sleep 0
	global_load_dword v133, v132, s[98:99] sc1
	s_waitcnt vmcnt(0)
	v_cmp_gt_u32_e32 vcc, s100, v133
	s_cbranch_vccnz .Lot_poll
	buffer_inv sc1
	s_waitcnt vmcnt(0)
	s_mov_b64 exec, -1

; #define LAS __attribute__((address_space(3)))
; template <class Epi, int LDA, int LDB, int KK>
; __device__ __forceinline__ void gemm_phase(int wv, LAS unsigned char* lds, const Gemm g, const StaticOrder& S, const Epi& E) {
;     ...
;           if constexpr (Epi::HAS_MID) { if (seg < Epi::NSEG - 1) E.mid(acc, cur, seg, wr, wc, fr, fq); }
;         }
;         E(acc, cur, wr, wc, fr, fq, (const LAS float*)(lds + 131072 + (ui % 3) * 1024));
.Lut_poll:
	s_sleep 0
	global_load_dword v149, v148, s[98:99] sc1
	s_waitcnt vmcnt(0)
	v_cmp_gt_u32_e32 vcc, s100, v149
	s_cbranch_vccnz .Lut_poll
	buffer_inv sc1
	s_waitcnt vmcnt(0)
	s_mov_b64 exec, -1
